# GEMM k-loop static priority given to waves 0-3 instead of waves 4-7
# baseline (speedup 1.0000x reference)
.LBB0_637:
	s_and_b64 s[2:3], s[8:9], exec
	v_readlane_b32 s2, v255, 26
	v_readlane_b32 s4, v255, 30
	v_readlane_b32 s3, v255, 27
	v_readlane_b32 s5, v255, 31
	s_cselect_b32 s24, s5, s3
	s_cselect_b32 s28, s4, s2
	v_readlane_b32 s2, v255, 24
	v_readlane_b32 s4, v255, 32
	v_readlane_b32 s3, v255, 25
	v_readlane_b32 s5, v255, 33
	s_cselect_b32 s29, s5, s3
	s_cselect_b32 s34, s4, s2
	v_readlane_b32 s2, v255, 23
	v_readlane_b32 s3, v255, 43
	s_cselect_b32 s14, s3, s2
	v_readlane_b32 s2, v255, 39
	s_cselect_b32 s39, s2, 0
	v_readlane_b32 s2, v255, 18
	v_readlane_b32 s3, v255, 40
	s_cselect_b32 s44, s3, s2
	s_lshl_b32 s45, s15, 8
	s_mul_i32 s2, s15, 0xfe
	s_add_i32 s45, s45, s39
	s_lshl_b32 s6, s47, 8
	s_add_i32 s4, s2, -1
	s_cmp_eq_u32 s44, 7
	s_cselect_b64 vcc, -1, 0
	s_and_b64 s[2:3], vcc, exec
	s_cselect_b32 s2, 0, s45
	s_cselect_b32 s40, s4, 0
	s_ashr_i32 s3, s2, 31
	v_mov_b32_e32 v175, v163
	s_mul_i32 s3, s3, s14
	s_mul_hi_u32 s4, s2, s14
	s_ashr_i32 s7, s6, 31
	s_add_i32 s3, s4, s3
	s_waitcnt vmcnt(1)
	v_ashrrev_i32_e32 v10, 6, v175
	s_waitcnt vmcnt(0)
	v_bfe_u32 v14, v175, 3, 3
	s_mul_i32 s2, s2, s14
	s_mul_i32 s4, s7, s14
	s_mul_hi_u32 s5, s6, s14
	v_lshl_or_b32 v6, v10, 5, v14
	s_add_i32 s5, s5, s4
	v_and_b32_e32 v0, 63, v175
	s_lshl_b64 s[2:3], s[2:3], 1
	s_mul_i32 s4, s6, s14
	s_add_u32 s2, s28, s2
	v_lshlrev_b32_e32 v176, 4, v0
	v_add_u32_e32 v0, s40, v6
	s_addc_u32 s3, s24, s3
	s_lshl_b64 s[4:5], s[4:5], 1
	v_med3_i32 v0, v0, 0, v211
	s_add_u32 s4, s34, s4
	v_cndmask_b32_e32 v0, v6, v0, vcc
	s_addc_u32 s5, s29, s5
	v_bfe_u32 v223, v175, 4, 2
	v_mad_u64_u32 v[166:167], s[28:29], v0, s14, 0
	v_xor_b32_e32 v4, v223, v175
	v_ashrrev_i32_e32 v2, 31, v0
	v_mov_b32_e32 v0, v167
	v_mad_u64_u32 v[2:3], s[28:29], v2, s14, v[0:1]
	v_lshlrev_b32_e32 v0, 3, v4
	v_lshlrev_b32_e32 v15, 2, v10
	v_and_b32_e32 v0, 56, v0
	v_lshlrev_b32_e32 v177, 12, v10
	v_lshlrev_b32_e32 v130, 1, v0
	v_ashrrev_i32_e32 v0, 31, v10
	v_or_b32_e32 v17, v176, v177
	v_or_b32_e32 v18, 1, v15
	v_and_b32_e32 v174, 3, v10
	v_mul_lo_u32 v16, v0, s14
	v_readfirstlane_b32 s15, v17
	v_add_u32_e32 v0, 0x8000, v17
	v_lshl_or_b32 v10, v18, 3, v14
	v_mov_b32_e32 v167, v2
	v_mad_u64_u32 v[168:169], s[28:29], v6, s14, 0
	s_mov_b32 m0, s15
	v_readfirstlane_b32 s15, v0
	v_add_u32_e32 v0, s40, v10
	v_lshl_add_u64 v[2:3], v[166:167], 1, s[2:3]
	v_mov_b32_e32 v131, v1
	v_add_u32_e32 v169, v169, v16
	v_med3_i32 v0, v0, 0, v211
	v_lshl_add_u64 v[4:5], v[2:3], 0, v[130:131]
	v_lshl_add_u64 v[6:7], v[168:169], 1, s[4:5]
	v_cndmask_b32_e32 v0, v10, v0, vcc
	v_lshl_add_u64 v[8:9], v[6:7], 0, v[130:131]
	global_load_lds_dwordx4 v[4:5], off
	s_mov_b32 m0, s15
	v_lshrrev_b32_e32 v4, 1, v10
	v_mad_u64_u32 v[170:171], s[28:29], v0, s14, 0
	global_load_lds_dwordx4 v[8:9], off
	v_xor_b32_e32 v8, v4, v175
	v_ashrrev_i32_e32 v4, 31, v0
	v_mov_b32_e32 v0, v171
	v_mad_u64_u32 v[4:5], s[28:29], v4, s14, v[0:1]
	v_lshlrev_b32_e32 v0, 3, v8
	v_lshlrev_b32_e32 v178, 10, v18
	v_mov_b32_e32 v171, v4
	v_and_b32_e32 v0, 56, v0
	v_mad_u64_u32 v[172:173], s[28:29], v10, s14, 0
	v_or_b32_e32 v18, v176, v178
	v_lshl_add_u64 v[4:5], v[170:171], 1, s[2:3]
	v_lshlrev_b32_e32 v132, 1, v0
	v_mov_b32_e32 v133, v1
	v_add_u32_e32 v173, v173, v16
	v_readfirstlane_b32 s15, v18
	v_add_u32_e32 v0, 0x8000, v18
	v_lshl_add_u64 v[8:9], v[4:5], 0, v[132:133]
	v_lshl_add_u64 v[10:11], v[172:173], 1, s[4:5]
	s_mov_b32 m0, s15
	v_readfirstlane_b32 s15, v0
	s_waitcnt lgkmcnt(0)
	v_lshl_add_u64 v[12:13], v[10:11], 0, v[132:133]
	global_load_lds_dwordx4 v[8:9], off
	s_mov_b32 m0, s15
	v_or_b32_e32 v19, 2, v15
	global_load_lds_dwordx4 v[12:13], off
	v_lshl_or_b32 v12, v19, 3, v14
	v_add_u32_e32 v0, s40, v12
	v_med3_i32 v0, v0, 0, v211
	v_cndmask_b32_e32 v0, v12, v0, vcc
	v_lshrrev_b32_e32 v8, 1, v12
	v_mad_u64_u32 v[154:155], s[28:29], v0, s14, 0
	v_xor_b32_e32 v13, v8, v175
	v_ashrrev_i32_e32 v8, 31, v0
	v_mov_b32_e32 v0, v155
	v_mad_u64_u32 v[8:9], s[28:29], v8, s14, v[0:1]
	v_lshlrev_b32_e32 v0, 3, v13
	v_lshlrev_b32_e32 v179, 10, v19
	v_mov_b32_e32 v155, v8
	v_and_b32_e32 v0, 56, v0
	v_or_b32_e32 v19, v176, v179
	v_lshl_add_u64 v[8:9], v[154:155], 1, s[2:3]
	v_lshlrev_b32_e32 v0, 1, v0
	v_readfirstlane_b32 s15, v19
	v_lshl_add_u64 v[8:9], v[8:9], 0, v[0:1]
	v_mad_u64_u32 v[156:157], s[28:29], v12, s14, 0
	s_mov_b32 m0, s15
	v_add_u32_e32 v157, v157, v16
	global_load_lds_dwordx4 v[8:9], off
	v_add_u32_e32 v8, 0x8000, v19
	v_lshl_add_u64 v[12:13], v[156:157], 1, s[4:5]
	v_readfirstlane_b32 s15, v8
	v_lshl_add_u64 v[12:13], v[12:13], 0, v[0:1]
	s_mov_b32 m0, s15
	v_or_b32_e32 v15, 3, v15
	global_load_lds_dwordx4 v[12:13], off
	v_lshl_or_b32 v12, v15, 3, v14
	v_add_u32_e32 v8, s40, v12
	v_med3_i32 v8, v8, 0, v211
	v_cndmask_b32_e32 v8, v12, v8, vcc
	v_lshrrev_b32_e32 v9, 1, v12
	v_mad_u64_u32 v[158:159], s[28:29], v8, s14, 0
	v_xor_b32_e32 v13, v9, v175
	v_ashrrev_i32_e32 v9, 31, v8
	v_mov_b32_e32 v8, v159
	v_mad_u64_u32 v[8:9], s[28:29], v9, s14, v[8:9]
	v_lshlrev_b32_e32 v13, 3, v13
	v_lshlrev_b32_e32 v180, 10, v15
	v_mov_b32_e32 v159, v8
	v_and_b32_e32 v13, 56, v13
	v_or_b32_e32 v14, v176, v180
	v_lshl_add_u64 v[8:9], v[158:159], 1, s[2:3]
	v_lshlrev_b32_e32 v160, 1, v13
	v_mov_b32_e32 v161, v1
	v_readfirstlane_b32 s15, v14
	v_lshl_add_u64 v[8:9], v[8:9], 0, v[160:161]
	v_mad_u64_u32 v[164:165], s[28:29], v12, s14, 0
	s_mov_b32 m0, s15
	v_add_u32_e32 v165, v165, v16
	global_load_lds_dwordx4 v[8:9], off
	v_add_u32_e32 v8, 0x8000, v14
	s_cmpk_gt_u32 s14, 0x7f
	v_lshl_add_u64 v[12:13], v[164:165], 1, s[4:5]
	v_readfirstlane_b32 s15, v8
	s_cselect_b32 s34, 0x80, 0
	v_add_u32_e32 v8, 0x10000, v17
	v_lshl_add_u64 v[12:13], v[12:13], 0, v[160:161]
	s_mov_b32 m0, s15
	v_lshl_add_u64 v[2:3], v[2:3], 0, s[34:35]
	v_readfirstlane_b32 s15, v8
	global_load_lds_dwordx4 v[12:13], off
	v_lshl_add_u64 v[2:3], v[2:3], 0, v[130:131]
	s_mov_b32 m0, s15
	v_mov_b32_e32 v127, 0
	v_mov_b32_e32 v128, 0
	v_mov_b32_e32 v129, 0
	v_mov_b32_e32 v122, 0
	v_mov_b32_e32 v123, 0
	v_mov_b32_e32 v124, 0
	v_mov_b32_e32 v125, 0
	v_mov_b32_e32 v118, 0
	v_mov_b32_e32 v119, 0
	v_mov_b32_e32 v120, 0
	v_mov_b32_e32 v121, 0
	v_mov_b32_e32 v114, 0
	v_mov_b32_e32 v115, 0
	v_mov_b32_e32 v116, 0
	v_mov_b32_e32 v117, 0
	v_mov_b32_e32 v110, 0
	v_mov_b32_e32 v111, 0
	v_mov_b32_e32 v112, 0
	v_mov_b32_e32 v113, 0
	v_mov_b32_e32 v106, 0
	v_mov_b32_e32 v107, 0
	v_mov_b32_e32 v108, 0
	v_mov_b32_e32 v109, 0
	v_mov_b32_e32 v102, 0
	v_mov_b32_e32 v103, 0
	v_mov_b32_e32 v104, 0
	v_mov_b32_e32 v105, 0
	v_mov_b32_e32 v98, 0
	v_mov_b32_e32 v99, 0
	v_mov_b32_e32 v100, 0
	v_mov_b32_e32 v101, 0
	v_mov_b32_e32 v94, 0
	v_mov_b32_e32 v95, 0
	v_mov_b32_e32 v96, 0
	v_mov_b32_e32 v97, 0
	v_mov_b32_e32 v90, 0
	v_mov_b32_e32 v91, 0
	v_mov_b32_e32 v92, 0
	v_mov_b32_e32 v93, 0
	v_mov_b32_e32 v86, 0
	v_mov_b32_e32 v87, 0
	v_mov_b32_e32 v88, 0
	v_mov_b32_e32 v89, 0
	v_mov_b32_e32 v82, 0
	v_mov_b32_e32 v83, 0
	v_mov_b32_e32 v84, 0
	v_mov_b32_e32 v85, 0
	v_mov_b32_e32 v78, 0
	v_mov_b32_e32 v79, 0
	v_mov_b32_e32 v80, 0
	v_mov_b32_e32 v81, 0
	v_mov_b32_e32 v74, 0
	v_mov_b32_e32 v75, 0
	v_mov_b32_e32 v76, 0
	v_mov_b32_e32 v77, 0
	v_mov_b32_e32 v70, 0
	v_mov_b32_e32 v71, 0
	v_mov_b32_e32 v72, 0
	v_mov_b32_e32 v73, 0
	v_mov_b32_e32 v66, 0
	v_mov_b32_e32 v67, 0
	v_mov_b32_e32 v68, 0
	v_mov_b32_e32 v69, 0
	v_mov_b32_e32 v62, 0
	v_mov_b32_e32 v63, 0
	v_mov_b32_e32 v64, 0
	v_mov_b32_e32 v65, 0
	v_mov_b32_e32 v58, 0
	v_mov_b32_e32 v59, 0
	v_mov_b32_e32 v60, 0
	v_mov_b32_e32 v61, 0
	v_mov_b32_e32 v54, 0
	v_mov_b32_e32 v55, 0
	v_mov_b32_e32 v56, 0
	v_mov_b32_e32 v57, 0
	v_mov_b32_e32 v50, 0
	v_mov_b32_e32 v51, 0
	v_mov_b32_e32 v52, 0
	v_mov_b32_e32 v53, 0
	v_mov_b32_e32 v46, 0
	v_mov_b32_e32 v47, 0
	v_mov_b32_e32 v48, 0
	v_mov_b32_e32 v49, 0
	v_mov_b32_e32 v42, 0
	v_mov_b32_e32 v43, 0
	v_mov_b32_e32 v44, 0
	v_mov_b32_e32 v45, 0
	v_mov_b32_e32 v34, 0
	v_mov_b32_e32 v35, 0
	v_mov_b32_e32 v36, 0
	v_mov_b32_e32 v37, 0
	v_mov_b32_e32 v30, 0
	v_mov_b32_e32 v31, 0
	v_mov_b32_e32 v32, 0
	v_mov_b32_e32 v33, 0
	v_mov_b32_e32 v38, 0
	v_mov_b32_e32 v39, 0
	v_mov_b32_e32 v40, 0
	v_mov_b32_e32 v41, 0
	v_mov_b32_e32 v26, 0
	v_mov_b32_e32 v27, 0
	v_mov_b32_e32 v28, 0
	v_mov_b32_e32 v29, 0
	v_mov_b32_e32 v22, 0
	v_mov_b32_e32 v23, 0
	v_mov_b32_e32 v24, 0
	v_mov_b32_e32 v25, 0
	v_mov_b32_e32 v19, 0
	v_mov_b32_e32 v20, 0
	v_mov_b32_e32 v21, 0
	v_mov_b32_e32 v14, 0
	v_mov_b32_e32 v15, 0
	v_mov_b32_e32 v16, 0
	v_mov_b32_e32 v12, 0
	v_mov_b32_e32 v13, 0
	s_waitcnt vmcnt(0)
	s_waitcnt vmcnt(0) lgkmcnt(0)
	s_barrier
	global_load_lds_dwordx4 v[2:3], off
	v_add_u32_e32 v2, 0x18000, v17
	v_lshl_add_u64 v[6:7], v[6:7], 0, s[34:35]
	v_readfirstlane_b32 s15, v2
	v_lshl_add_u64 v[6:7], v[6:7], 0, v[130:131]
	s_mov_b32 m0, s15
	v_lshl_add_u64 v[2:3], v[4:5], 0, s[34:35]
	global_load_lds_dwordx4 v[6:7], off
	v_add_u32_e32 v6, 0x10000, v18
	v_lshl_add_u64 v[2:3], v[2:3], 0, v[132:133]
	v_readfirstlane_b32 s15, v6
	s_mov_b32 m0, s15
	v_lshl_add_u64 v[4:5], v[10:11], 0, s[34:35]
	global_load_lds_dwordx4 v[2:3], off
	v_add_u32_e32 v2, 0x18000, v18
	v_lshl_add_u64 v[4:5], v[4:5], 0, v[132:133]
	v_readfirstlane_b32 s15, v2
	s_mov_b32 m0, s15
	v_and_b32_e32 v134, 15, v175
	global_load_lds_dwordx4 v[4:5], off
	v_ashrrev_i32_e32 v2, 1, v175
	s_movk_i32 s15, 0xff80
	v_mov_b32_e32 v5, 0
	v_and_or_b32 v225, v2, s15, v134
	v_lshlrev_b32_e32 v224, 6, v174
	s_cmp_lt_u32 s14, 64
	v_readlane_b32 s51, v255, 37
	v_readlane_b32 s52, v255, 38
	s_cbranch_scc1 .Lgemm_skip_zero_a
	v_lshrrev_b32_e32 v10, 1, v134
	v_or_b32_e32 v2, v224, v134
	v_lshlrev_b32_e32 v182, 7, v2
	v_xor_b32_e32 v2, v223, v10
	v_lshlrev_b32_e32 v181, 7, v225
	v_lshlrev_b32_e32 v183, 4, v2
	v_or_b32_e32 v11, v181, v183
	v_or_b32_e32 v244, v182, v183
	v_lshl_add_u32 v240, v166, 1, v130
	v_lshl_add_u32 v241, v168, 1, v130
	v_lshl_add_u32 v242, v170, 1, v132
	v_lshl_add_u32 v243, v172, 1, v132
	ds_read_b128 v[150:153], v11
	ds_read_b128 v[146:149], v11 offset:2048
	ds_read_b128 v[142:145], v244 offset:32768
	ds_read_b128 v[138:141], v244 offset:34816
	ds_read_b128 v[134:137], v244 offset:36864
	ds_read_b128 v[200:203], v11 offset:4096
	ds_read_b128 v[130:133], v244 offset:38912
	ds_read_b128 v[236:239], v11 offset:6144
	s_lshr_b32 s14, s14, 6
	v_bitop3_b32 v10, v223, v10, 4 bitop3:0x36
	v_mov_b32_e32 v126, 0
	s_add_i32 s15, s14, -1
	v_lshlrev_b32_e32 v184, 4, v10
	s_mov_b32 s24, 0
	s_mov_b32 s28, 0
	v_mov_b32_e32 v161, v1
	v_lshl_add_u64 v[154:155], v[154:155], 1, v[0:1]
	v_lshl_add_u64 v[156:157], v[156:157], 1, v[0:1]
	v_lshl_add_u64 v[158:159], v[158:159], 1, v[160:161]
	v_lshl_add_u64 v[164:165], v[164:165], 1, v[160:161]
	v_readfirstlane_b32 s100, v179
	v_readfirstlane_b32 s101, v180
	v_readfirstlane_b32 s32, v178
	v_readfirstlane_b32 s41, v177
	s_lshl_b32 s32, s32, 16
	s_or_b32 s32, s32, s41
	v_readfirstlane_b32 s41, v163
	s_bitcmp1_b32 s41, 8
	s_cbranch_scc1 .Lgemm_prio_done
	s_setprio 1
